# GDN scan: loader waves + LDS flag hand-off for the sample slab (24 scan workgroups), single-wave register ring for prompt slabs
# speedup vs baseline: 1.0047x; 1.0047x over previous
; DI f32x16 zero16() { f32x16 z; for (int i = 0; i < 16; ++i) z[i] = 0.f; return z; }
; DI void phase_scan(KArgs args, LAS unsigned char* L, const Ctx& c) {
;     if (c.slab == NSLAB - 1 && c.bid >= 24 && c.bid < 40) { phase_select(args, L, c, c.bid - 24); return; }
;     const int nwu = c.nseq * 24, wu = c.bid;
;     if (wu < nwu && c.wave == 0) {
;         const int lane = c.lane;
;         const int chain = wu >> 1, nt = wu & 1, seq = chain / 12, rem = chain % 12, head = rem >> 1, dir = rem & 1;
;         const int nch = c.seqlen >> 6, gch0 = seq * nch;
;         unsigned char* GS = BIGP(unsigned char, B_GSCR);
;         f32x16 S[2]; S[0] = zero16(); S[1] = zero16();
;         bf16x8 A[2][2][4]; u32x4 cm[2][2][2];
;         const long gstep = (long)(dir ? -1 : 1) * 12 * GSTRIDE;
;         const unsigned char* G0 = GS + (size_t)(((gch0 + (dir ? nch - 1 : 0)) * 6 + head) * 2 + dir) * GSTRIDE;
;         unsigned char* Gs = (unsigned char*)G0;
;         float glv[4];
; #pragma unroll
;         for (int q = 0; q < 4; ++q) { const int sq = q * 64 + lane; glv[q] = *(const float*)(G0 + (long)(sq < nch ? sq : nch - 1) * gstep + 40960); }
.LBB0_646:
	s_movk_i32 s33, 0x600
	s_and_b64 vcc, exec, s[0:1]
	s_cbranch_vccz .LBB0_946
	v_readlane_b32 s2, v254, 23
	s_lshr_b32 s30, s60, 6
	v_readlane_b32 s3, v254, 24
	s_and_b64 s[0:1], s[2:3], exec
	s_cselect_b32 s0, 6, 8
	s_add_i32 s31, s30, -1
	v_writelane_b32 v254, s0, 32
	s_and_b64 s[0:1], s[2:3], exec
	s_cselect_b32 s2, 0xc0, 24
	s_cselect_b32 s3, 64, 0x100
	s_cmp_lt_u32 s61, s3
	s_cselect_b64 s[0:1], -1, 0
	s_cmp_lt_i32 s68, s2
	s_cselect_b64 s[2:3], -1, 0
	s_and_b64 s[0:1], s[2:3], s[0:1]
	s_andn2_b64 vcc, exec, s[0:1]
	s_movk_i32 s27, 0x90
	v_readlane_b32 s28, v254, 27
	v_readlane_b32 s29, v254, 29
	s_cbranch_vccnz .LBB0_651
	s_setprio 3
	s_ashr_i32 s0, s68, 1
	s_mul_hi_i32 s1, s0, 0x2aaaaaab
	s_lshr_b32 s2, s1, 31
	s_ashr_i32 s1, s1, 1
	s_add_i32 s1, s1, s2
	s_mul_i32 s2, s1, 12
	s_sub_i32 s2, s0, s2
	v_readlane_b32 s4, v254, 32
	s_bfe_i32 s3, s2, 0x10000
	s_and_b32 s0, s2, 1
	s_lshl_b32 s4, s1, s4
	s_cmp_eq_u32 s0, 0
	s_mov_b32 s0, 0x78c00
	s_cselect_b32 s1, 0, -1
	s_cselect_b32 s0, s0, 0xfff87400
	s_and_b32 s3, s3, s31
	s_add_i32 s3, s3, s4
	s_mul_i32 s3, s3, 12
	s_add_i32 s24, s3, s2
	s_mul_hi_i32 s23, s24, 0xa100
	s_mul_i32 s24, s24, 0xa100
	s_waitcnt lgkmcnt(0)
	s_add_u32 s6, s72, s24
	s_addc_u32 s7, s73, s23
	s_add_u32 s2, s6, 0x37800000
	s_addc_u32 s3, s7, 0
	v_min_i32_e32 v1, s31, v28
	v_mov_b64_e32 v[4:5], s[2:3]
	v_mad_u64_u32 v[6:7], s[4:5], s0, v1, v[4:5]
	v_mad_i32_i24 v1, s1, v1, v7
	v_or_b32_e32 v7, 64, v28
	v_min_i32_e32 v2, s31, v7
	v_mad_u64_u32 v[8:9], s[4:5], s0, v2, v[4:5]
	v_or_b32_e32 v12, 0x80, v28
	v_mad_i32_i24 v9, s1, v2, v9
	v_min_i32_e32 v2, s31, v12
	v_mad_u64_u32 v[10:11], s[4:5], s0, v2, v[4:5]
	v_or_b32_e32 v13, 0xc0, v28
	v_mad_i32_i24 v11, s1, v2, v11
	v_min_i32_e32 v2, s31, v13
	v_mad_u64_u32 v[4:5], s[4:5], s0, v2, v[4:5]
	s_add_u32 s20, s6, 0x37802000
	s_addc_u32 s21, s7, 0
	s_lshl_b32 s4, s68, 12
	s_and_b32 s25, s4, 0x1000
	s_add_u32 s18, s2, s0
	s_addc_u32 s19, s3, s1
	s_add_u32 s16, s18, 0x2000
	s_addc_u32 s17, s19, 0
	s_add_u32 s14, s18, s0
	s_addc_u32 s15, s19, s1
	s_add_u32 s12, s14, 0x2000
	s_addc_u32 s13, s15, 0
	s_add_u32 s10, s14, s0
	s_addc_u32 s11, s15, s1
	s_mov_b32 s26, 0xa000
	s_add_u32 s8, s10, 0x2000
	v_add_co_u32_e32 v6, vcc, s26, v6
	v_lshlrev_b32_e32 v148, 4, v7
	s_addc_u32 s9, s11, 0
	v_addc_co_u32_e32 v7, vcc, 0, v1, vcc
	s_add_u32 s6, s10, s0
	v_add_co_u32_e32 v8, vcc, s26, v8
	s_addc_u32 s7, s11, s1
	s_nop 0
	v_addc_co_u32_e32 v9, vcc, 0, v9, vcc
	s_add_u32 s4, s6, 0x2000
	v_add_co_u32_e32 v10, vcc, s26, v10
	s_addc_u32 s5, s7, 0
	s_add_i32 s22, 0, 0x14000
	v_addc_co_u32_e32 v11, vcc, 0, v11, vcc
	v_mad_i32_i24 v5, s1, v2, v5
	v_lshlrev_b32_e32 v2, 4, v28
	v_add_co_u32_e32 v4, vcc, s26, v4
	v_addc_co_u32_e32 v5, vcc, 0, v5, vcc
	global_load_dword v1, v[6:7], off
	global_load_dword v168, v[8:9], off
	global_load_dword v169, v[10:11], off
	global_load_dword v170, v[4:5], off
	v_lshlrev_b32_e32 v150, 4, v12
	v_lshlrev_b32_e32 v152, 4, v13
	v_or_b32_e32 v154, 0x1000, v2
	v_or_b32_e32 v156, 0x1400, v2
	v_or_b32_e32 v158, 0x1800, v2
	v_or_b32_e32 v160, 0x1c00, v2
	v_lshl_or_b32 v162, v28, 5, s25
	v_mov_b32_e32 v163, v3
	v_lshl_add_u64 v[12:13], s[20:21], 0, v[162:163]
	v_lshl_add_u64 v[12:13], v[12:13], 0, 16
	v_or_b32_e32 v164, 0x800, v162
	v_mov_b32_e32 v165, v3
	v_lshl_add_u64 v[14:15], s[20:21], 0, v[164:165]
	v_lshl_add_u64 v[14:15], v[14:15], 0, 16
	v_lshl_add_u64 v[16:17], s[16:17], 0, v[162:163]
	v_lshl_add_u64 v[16:17], v[16:17], 0, 16
	v_lshl_add_u64 v[18:19], s[16:17], 0, v[164:165]
	v_lshl_add_u64 v[18:19], v[18:19], 0, 16
	v_lshl_add_u64 v[20:21], s[12:13], 0, v[162:163]
	v_lshl_add_u64 v[20:21], v[20:21], 0, 16
	v_lshl_add_u64 v[22:23], s[12:13], 0, v[164:165]
	v_lshl_add_u64 v[22:23], v[22:23], 0, 16
	v_lshl_add_u64 v[24:25], s[8:9], 0, v[162:163]
	v_lshl_add_u64 v[24:25], v[24:25], 0, 16
	v_lshl_add_u64 v[26:27], s[8:9], 0, v[164:165]
	v_lshl_add_u64 v[26:27], v[26:27], 0, 16
	v_lshl_add_u64 v[28:29], s[4:5], 0, v[162:163]
	v_lshl_add_u64 v[28:29], v[28:29], 0, 16
	v_lshl_add_u64 v[30:31], s[4:5], 0, v[164:165]
	v_lshl_add_u64 v[30:31], v[30:31], 0, 16
	s_add_u32 s4, s24, s25
	s_addc_u32 s5, s23, 0
	s_add_u32 s4, s72, s4
	s_addc_u32 s5, s73, s5
	v_lshl_add_u64 v[4:5], s[4:5], 0, v[2:3]
	s_mov_b64 s[4:5], 0x37808800
	v_lshl_add_u64 v[166:167], v[4:5], 0, s[4:5]
	v_mov_b32_e32 v4, 0
	v_mov_b32_e32 v149, v3
	v_mov_b32_e32 v151, v3
	v_mov_b32_e32 v153, v3
	v_mov_b32_e32 v155, v3
	v_mov_b32_e32 v157, v3
	v_mov_b32_e32 v159, v3
	v_mov_b32_e32 v161, v3
	s_lshl_b64 s[8:9], s[0:1], 1
	v_mov_b32_e32 v5, v4
	v_mov_b32_e32 v6, v4
	v_mov_b32_e32 v7, v4
	v_mov_b32_e32 v8, v4
	v_mov_b32_e32 v9, v4
	v_mov_b32_e32 v10, v4
	v_mov_b32_e32 v11, v4
	v_mov_b32_e32 v12, v4
	v_mov_b32_e32 v13, v4
	v_mov_b32_e32 v14, v4
	v_mov_b32_e32 v15, v4
	v_mov_b32_e32 v16, v4
	v_mov_b32_e32 v17, v4
	v_mov_b32_e32 v18, v4
	v_mov_b32_e32 v19, v4
	v_mov_b32_e32 v20, v4
	v_mov_b32_e32 v21, v4
	v_mov_b32_e32 v22, v4
	v_mov_b32_e32 v23, v4
	v_mov_b32_e32 v24, v4
	v_mov_b32_e32 v25, v4
	v_mov_b32_e32 v26, v4
	v_mov_b32_e32 v27, v4
	v_mov_b32_e32 v28, v4
	v_mov_b32_e32 v29, v4
	v_mov_b32_e32 v30, v4
	v_mov_b32_e32 v31, v4
	v_mov_b32_e32 v32, v4
	v_mov_b32_e32 v33, v4
	v_mov_b32_e32 v34, v4
	v_mov_b32_e32 v35, v4
	v_mov_b32_e32 v173, 0x24e00
	s_lshr_b32 s6, s61, 6
	s_cmp_lg_u32 s6, 0
	s_cbranch_scc1 .Lsc_isloader
	v_readlane_b32 s7, v254, 23
	s_nop 1
	s_cmp_lg_u32 s7, 0
	s_cbranch_scc1 .Lsc_self
	s_branch .Lsc_consumer
; DI void phase_scan(KArgs args, LAS unsigned char* L, const Ctx& c) {
;     ...
;         SCAN_DMA(); SCAN_DMA(); SCAN_DMA(); SCAN_DMA(); SCAN_DMA();
;         asm volatile("s_waitcnt vmcnt(48)" ::: "memory"); SCAN_LOAD(0);
;         asm volatile("s_waitcnt vmcnt(36)" ::: "memory"); SCAN_LOAD(1);
.Lsc_isloader:
	s_add_i32 s7, s6, -1
	s_lshl_b32 s20, s7, 12
	s_lshl_b32 s7, s7, 2
	v_add_u32_e32 v246, s7, v173
	s_cmp_eq_u32 s6, 3
	s_cbranch_scc1 .Lsc_loader_c
	s_branch .Lsc_loader_a
.Lsc_self:
	s_mov_b64 s[12:13], s[2:3]
	s_mov_b32 s11, 0
	s_mov_b32 s10, 0
	s_add_u32 s14, s12, 0x1000
	s_addc_u32 s15, s13, 0
	s_add_u32 s16, s12, 0x2000
	s_addc_u32 s17, s13, 0
	global_load_dwordx4 v[36:39], v2, s[12:13]
	global_load_dwordx4 v[40:43], v2, s[12:13] offset:1024
	global_load_dwordx4 v[44:47], v2, s[12:13] offset:2048
	global_load_dwordx4 v[48:51], v2, s[12:13] offset:3072
	global_load_dwordx4 v[52:55], v2, s[14:15]
	global_load_dwordx4 v[56:59], v2, s[14:15] offset:1024
	global_load_dwordx4 v[60:63], v2, s[14:15] offset:2048
	global_load_dwordx4 v[64:67], v2, s[14:15] offset:3072
	global_load_dwordx4 v[68:71], v162, s[16:17]
	global_load_dwordx4 v[72:75], v162, s[16:17] offset:16
	global_load_dwordx4 v[76:79], v164, s[16:17]
	global_load_dwordx4 v[80:83], v164, s[16:17] offset:16
	s_add_i32 s11, s11, 1
	s_cmp_le_u32 s11, s31
	s_cselect_b32 s6, s0, 0
	s_cselect_b32 s7, s1, 0
	s_add_u32 s12, s12, s6
	s_addc_u32 s13, s13, s7
	s_add_u32 s14, s12, 0x1000
	s_addc_u32 s15, s13, 0
	s_add_u32 s16, s12, 0x2000
	s_addc_u32 s17, s13, 0
	global_load_dwordx4 v[84:87], v2, s[12:13]
	global_load_dwordx4 v[88:91], v2, s[12:13] offset:1024
	global_load_dwordx4 v[92:95], v2, s[12:13] offset:2048
	global_load_dwordx4 v[96:99], v2, s[12:13] offset:3072
	global_load_dwordx4 v[100:103], v2, s[14:15]
	global_load_dwordx4 v[104:107], v2, s[14:15] offset:1024
	global_load_dwordx4 v[108:111], v2, s[14:15] offset:2048
	global_load_dwordx4 v[112:115], v2, s[14:15] offset:3072
	global_load_dwordx4 v[116:119], v162, s[16:17]
	global_load_dwordx4 v[120:123], v162, s[16:17] offset:16
	global_load_dwordx4 v[124:127], v164, s[16:17]
	global_load_dwordx4 v[128:131], v164, s[16:17] offset:16
	s_add_i32 s11, s11, 1
	s_cmp_le_u32 s11, s31
	s_cselect_b32 s6, s0, 0
	s_cselect_b32 s7, s1, 0
	s_add_u32 s12, s12, s6
	s_addc_u32 s13, s13, s7
	s_add_u32 s14, s12, 0x1000
	s_addc_u32 s15, s13, 0
	s_add_u32 s16, s12, 0x2000
	s_addc_u32 s17, s13, 0
	global_load_dwordx4 v[178:181], v2, s[12:13]
	global_load_dwordx4 v[182:185], v2, s[12:13] offset:1024
	global_load_dwordx4 v[186:189], v2, s[12:13] offset:2048
	global_load_dwordx4 v[190:193], v2, s[12:13] offset:3072
	global_load_dwordx4 v[194:197], v2, s[14:15]
	global_load_dwordx4 v[198:201], v2, s[14:15] offset:1024
	global_load_dwordx4 v[202:205], v2, s[14:15] offset:2048
	global_load_dwordx4 v[226:229], v2, s[14:15] offset:3072
	global_load_dwordx4 v[230:233], v162, s[16:17]
	global_load_dwordx4 v[234:237], v162, s[16:17] offset:16
	global_load_dwordx4 v[238:241], v164, s[16:17]
	global_load_dwordx4 v[242:245], v164, s[16:17] offset:16
	s_add_i32 s11, s11, 1
	s_cmp_le_u32 s11, s31
	s_cselect_b32 s6, s0, 0
	s_cselect_b32 s7, s1, 0
	s_add_u32 s12, s12, s6
	s_addc_u32 s13, s13, s7
	s_waitcnt vmcnt(12)

; DI void phase_scan(KArgs args, LAS unsigned char* L, const Ctx& c) {
;     ...
;         asm volatile("s_waitcnt vmcnt(0)" ::: "memory");
;     ...
;     }
;     attn_wave_units(args, L, c);
.Lscan_exit:
	s_waitcnt vmcnt(0)
	s_setprio 0
	s_branch .LBB0_651
